# conv LayerNorm statistics: halving butterfly via v_permlane32_swap / v_permlane16_swap / DPP row ops instead of select + ds_bpermute rounds (same operand pairs)
# speedup vs baseline: 1.0066x; 1.0066x over previous
.LBB0_462:
	s_add_i32 s19, s75, s76
	s_and_b32 s20, s19, 0x1c000
	v_add_u32_e32 v112, s20, v184
	ds_read2st64_b32 v[32:33], v112 offset1:8
	ds_read2st64_b32 v[34:35], v112 offset0:16 offset1:24
	s_add_i32 s21, s19, 0x4000
	s_and_b32 s21, s21, 0x1c000
	s_xor_b32 s20, s20, 0x10000
	s_waitcnt lgkmcnt(1)
	v_lshlrev_b32_e32 v152, 16, v32
	v_and_b32_e32 v153, 0xffff0000, v32
	v_lshlrev_b32_e32 v154, 16, v33
	v_and_b32_e32 v155, 0xffff0000, v33
	ds_read2st64_b32 v[32:33], v112 offset0:32 offset1:40
	ds_read2st64_b32 v[112:113], v112 offset0:48 offset1:56
	s_waitcnt lgkmcnt(2)
	v_lshlrev_b32_e32 v150, 16, v34
	v_and_b32_e32 v151, 0xffff0000, v34
	v_lshlrev_b32_e32 v142, 16, v35
	v_and_b32_e32 v143, 0xffff0000, v35
	s_waitcnt lgkmcnt(0)
	v_lshlrev_b32_e32 v34, 16, v112
	v_and_b32_e32 v35, 0xffff0000, v112
	v_add_u32_e32 v112, s21, v184
	s_add_i32 s21, s19, 0x4800
	s_and_b32 s21, s21, 0x1c800
	v_lshlrev_b32_e32 v130, 16, v32
	v_and_b32_e32 v131, 0xffff0000, v32
	v_lshlrev_b32_e32 v128, 16, v33
	v_and_b32_e32 v129, 0xffff0000, v33
	v_lshlrev_b32_e32 v32, 16, v113
	v_and_b32_e32 v33, 0xffff0000, v113
	v_add_u32_e32 v113, s21, v184
	s_add_i32 s21, s19, 0x5000
	s_and_b32 s21, s21, 0x1d000
	v_add_u32_e32 v114, s21, v184
	s_add_i32 s21, s19, 0x5800
	s_and_b32 s21, s21, 0x1d800
	v_add_u32_e32 v115, s21, v184
	s_add_i32 s21, s19, 0x6000
	s_and_b32 s21, s21, 0x1e000
	v_add_u32_e32 v116, s21, v184
	s_add_i32 s21, s19, 0x6800
	s_and_b32 s21, s21, 0x1e800
	v_add_u32_e32 v117, s21, v184
	s_add_i32 s21, s19, 0x7000
	s_and_b32 s21, s21, 0x1f000
	v_add_u32_e32 v118, s21, v184
	s_add_i32 s21, s19, 0x7800
	s_and_b32 s21, s21, 0x1f800
	v_add_u32_e32 v119, s21, v184
	s_add_i32 s21, s19, 0x8000
	s_and_b32 s21, s21, 0x1c000
	v_add_u32_e32 v132, s21, v184
	s_add_i32 s21, s19, 0x8800
	s_and_b32 s21, s21, 0x1c800
	v_add_u32_e32 v133, s21, v184
	s_add_i32 s21, s19, 0x9000
	s_and_b32 s21, s21, 0x1d000
	v_add_u32_e32 v134, s21, v184
	s_add_i32 s21, s19, 0x9800
	s_and_b32 s21, s21, 0x1d800
	v_add_u32_e32 v135, s21, v184
	s_add_i32 s21, s19, 0xa000
	s_and_b32 s21, s21, 0x1e000
	v_add_u32_e32 v136, s21, v184
	s_add_i32 s21, s19, 0xa800
	s_and_b32 s21, s21, 0x1e800
	v_add_u32_e32 v137, s21, v184
	s_add_i32 s21, s19, 0xb000
	s_and_b32 s21, s21, 0x1f000
	v_add_u32_e32 v138, s21, v184
	s_add_i32 s21, s19, 0xb800
	s_and_b32 s21, s21, 0x1f800
	v_add_u32_e32 v139, s21, v184
	s_add_i32 s21, s19, 0xc000
	s_and_b32 s21, s21, 0x1c000
	v_add_u32_e32 v156, s21, v184
	s_add_i32 s21, s19, 0xc800
	s_and_b32 s21, s21, 0x1c800
	v_add_u32_e32 v157, s21, v184
	s_add_i32 s21, s19, 0xd000
	s_and_b32 s21, s21, 0x1d000
	v_add_u32_e32 v158, s21, v184
	s_add_i32 s21, s19, 0xd800
	s_and_b32 s21, s21, 0x1d800
	v_add_u32_e32 v159, s21, v184
	s_add_i32 s21, s19, 0xe000
	s_and_b32 s21, s21, 0x1e000
	v_add_u32_e32 v160, s21, v184
	s_add_i32 s21, s19, 0xe800
	s_and_b32 s21, s21, 0x1e800
	v_add_u32_e32 v161, s21, v184
	s_add_i32 s21, s19, 0xf000
	s_and_b32 s21, s21, 0x1f000
	v_add_u32_e32 v172, s20, v184
	s_add_i32 s20, s19, 0x11000
	v_add_u32_e32 v162, s21, v184
	s_add_i32 s21, s19, 0xf800
	s_and_b32 s20, s20, 0x1d000
	s_and_b32 s21, s21, 0x1f800
	v_add_u32_e32 v174, s20, v184
	s_add_i32 s20, s18, -7
	v_add_u32_e32 v163, s21, v184
	s_ashr_i32 s21, s20, 31
	s_lshl_b64 s[46:47], s[20:21], 11
	s_add_i32 s20, s18, -6
	s_ashr_i32 s21, s20, 31
	s_lshl_b64 s[36:37], s[20:21], 11
	s_add_i32 s20, s18, -5
	s_ashr_i32 s21, s20, 31
	s_lshl_b64 s[34:35], s[20:21], 11
	s_add_i32 s20, s18, -4
	s_ashr_i32 s21, s20, 31
	s_add_i32 s19, s19, 0x12000
	s_lshl_b64 s[30:31], s[20:21], 11
	s_add_i32 s20, s18, -3
	ds_read_b32 v120, v112
	ds_read_b32 v121, v113
	ds_read_b32 v122, v114
	ds_read_b32 v123, v115
	ds_read_b32 v124, v116
	ds_read_b32 v125, v117
	ds_read_b32 v126, v118
	ds_read_b32 v127, v119
	ds_read_b32 v140, v132
	ds_read_b32 v141, v133
	ds_read_b32 v144, v134
	ds_read_b32 v145, v135
	ds_read_b32 v146, v136
	ds_read_b32 v147, v137
	ds_read_b32 v148, v138
	ds_read_b32 v149, v139
	ds_read_b32 v164, v156
	ds_read_b32 v165, v157
	ds_read_b32 v166, v158
	ds_read_b32 v167, v159
	ds_read_b32 v168, v160
	ds_read_b32 v169, v161
	ds_read_b32 v170, v162
	ds_read_b32 v171, v163
	ds_read_b32 v173, v172
	v_add_u32_e32 v172, s76, v208
	s_and_b32 s19, s19, 0x1e000
	s_ashr_i32 s21, s20, 31
	ds_read2st64_b32 v[178:179], v172 offset1:16
	v_add_u32_e32 v175, s19, v184
	ds_read_b32 v177, v174
	ds_read_b32 v183, v175
	ds_read_b32 v209, v172 offset:8192
	s_lshl_b64 s[28:29], s[20:21], 11
	s_add_i32 s20, s18, -2
	v_pk_fma_f32 v[152:153], v[98:99], v[152:153], v[100:101]
	s_ashr_i32 s21, s20, 31
	v_pk_fma_f32 v[152:153], v[38:39], v[154:155], v[152:153]
	v_pk_fma_f32 v[154:155], v[98:99], v[154:155], v[100:101]
	s_lshl_b64 s[26:27], s[20:21], 11
	s_add_i32 s20, s18, -1
	v_pk_fma_f32 v[152:153], v[40:41], v[150:151], v[152:153]
	v_pk_fma_f32 v[154:155], v[38:39], v[150:151], v[154:155]
	v_pk_fma_f32 v[150:151], v[98:99], v[150:151], v[100:101]
	s_ashr_i32 s21, s20, 31
	s_ashr_i32 s19, s18, 31
	v_pk_fma_f32 v[152:153], v[42:43], v[142:143], v[152:153]
	v_pk_fma_f32 v[154:155], v[40:41], v[142:143], v[154:155]
	v_pk_fma_f32 v[150:151], v[38:39], v[142:143], v[150:151]
	v_pk_fma_f32 v[142:143], v[98:99], v[142:143], v[100:101]
	v_lshl_add_u64 v[210:211], v[36:37], 0, s[46:47]
	v_lshl_add_u64 v[212:213], v[36:37], 0, s[36:37]
	s_lshl_b64 s[24:25], s[20:21], 11
	s_lshl_b64 s[20:21], s[18:19], 11
	v_pk_fma_f32 v[152:153], v[44:45], v[130:131], v[152:153]
	v_pk_fma_f32 v[154:155], v[42:43], v[130:131], v[154:155]
	v_pk_fma_f32 v[150:151], v[40:41], v[130:131], v[150:151]
	v_pk_fma_f32 v[142:143], v[38:39], v[130:131], v[142:143]
	v_pk_fma_f32 v[130:131], v[98:99], v[130:131], v[100:101]
	s_waitcnt lgkmcnt(3)
	v_lshlrev_b32_e32 v174, 16, v178
	v_and_b32_e32 v175, 0xffff0000, v178
	v_lshlrev_b32_e32 v180, 16, v179
	v_and_b32_e32 v181, 0xffff0000, v179
	s_waitcnt lgkmcnt(0)
	v_lshlrev_b32_e32 v178, 16, v209
	v_and_b32_e32 v179, 0xffff0000, v209
	v_lshl_add_u64 v[218:219], v[36:37], 0, s[34:35]
	v_lshl_add_u64 v[220:221], v[36:37], 0, s[30:31]
	v_lshl_add_u64 v[222:223], v[36:37], 0, s[28:29]
	v_lshl_add_u64 v[224:225], v[36:37], 0, s[26:27]
	v_lshl_add_u64 v[226:227], v[36:37], 0, s[24:25]
	v_lshl_add_u64 v[228:229], v[36:37], 0, s[20:21]
	global_load_dword v216, v[210:211], off nt
	global_load_dword v215, v[212:213], off nt
	global_load_dword v214, v[218:219], off nt
	s_nop 0
	global_load_dword v213, v[220:221], off nt
	global_load_dword v212, v[222:223], off nt
	global_load_dword v211, v[224:225], off nt
	global_load_dword v210, v[226:227], off nt
	global_load_dword v209, v[228:229], off nt
	v_pk_fma_f32 v[152:153], v[46:47], v[128:129], v[152:153]
	v_pk_fma_f32 v[154:155], v[44:45], v[128:129], v[154:155]
	v_pk_fma_f32 v[150:151], v[42:43], v[128:129], v[150:151]
	v_pk_fma_f32 v[142:143], v[40:41], v[128:129], v[142:143]
	v_pk_fma_f32 v[130:131], v[38:39], v[128:129], v[130:131]
	v_pk_fma_f32 v[128:129], v[98:99], v[128:129], v[100:101]
	v_pk_fma_f32 v[152:153], v[48:49], v[34:35], v[152:153]
	v_pk_fma_f32 v[154:155], v[46:47], v[34:35], v[154:155]
	v_pk_fma_f32 v[150:151], v[44:45], v[34:35], v[150:151]
	v_pk_fma_f32 v[142:143], v[42:43], v[34:35], v[142:143]
	v_pk_fma_f32 v[130:131], v[40:41], v[34:35], v[130:131]
	v_pk_fma_f32 v[128:129], v[38:39], v[34:35], v[128:129]
	v_pk_fma_f32 v[34:35], v[98:99], v[34:35], v[100:101]
	v_lshlrev_b32_e32 v112, 16, v120
	v_and_b32_e32 v113, 0xffff0000, v120
	v_pk_fma_f32 v[152:153], v[50:51], v[32:33], v[152:153]
	v_pk_fma_f32 v[154:155], v[48:49], v[32:33], v[154:155]
	v_pk_fma_f32 v[150:151], v[46:47], v[32:33], v[150:151]
	v_pk_fma_f32 v[142:143], v[44:45], v[32:33], v[142:143]
	v_pk_fma_f32 v[130:131], v[42:43], v[32:33], v[130:131]
	v_pk_fma_f32 v[128:129], v[40:41], v[32:33], v[128:129]
	v_pk_fma_f32 v[34:35], v[38:39], v[32:33], v[34:35]
	v_pk_fma_f32 v[32:33], v[98:99], v[32:33], v[100:101]
	v_lshlrev_b32_e32 v114, 16, v121
	v_and_b32_e32 v115, 0xffff0000, v121
	v_pk_fma_f32 v[152:153], v[52:53], v[112:113], v[152:153]
	v_pk_fma_f32 v[154:155], v[50:51], v[112:113], v[154:155]
	v_pk_fma_f32 v[150:151], v[48:49], v[112:113], v[150:151]
	v_pk_fma_f32 v[142:143], v[46:47], v[112:113], v[142:143]
	v_pk_fma_f32 v[130:131], v[44:45], v[112:113], v[130:131]
	v_pk_fma_f32 v[128:129], v[42:43], v[112:113], v[128:129]
	v_pk_fma_f32 v[34:35], v[40:41], v[112:113], v[34:35]
	v_pk_fma_f32 v[32:33], v[38:39], v[112:113], v[32:33]
	v_lshlrev_b32_e32 v116, 16, v122
	v_and_b32_e32 v117, 0xffff0000, v122
	v_pk_fma_f32 v[152:153], v[54:55], v[114:115], v[152:153]
	v_pk_fma_f32 v[154:155], v[52:53], v[114:115], v[154:155]
	v_pk_fma_f32 v[150:151], v[50:51], v[114:115], v[150:151]
	v_pk_fma_f32 v[142:143], v[48:49], v[114:115], v[142:143]
	v_pk_fma_f32 v[130:131], v[46:47], v[114:115], v[130:131]
	v_pk_fma_f32 v[128:129], v[44:45], v[114:115], v[128:129]
	v_pk_fma_f32 v[34:35], v[42:43], v[114:115], v[34:35]
	v_pk_fma_f32 v[32:33], v[40:41], v[114:115], v[32:33]
	v_lshlrev_b32_e32 v118, 16, v123
	v_and_b32_e32 v119, 0xffff0000, v123
	v_pk_fma_f32 v[152:153], v[56:57], v[116:117], v[152:153]
	v_pk_fma_f32 v[154:155], v[54:55], v[116:117], v[154:155]
	v_pk_fma_f32 v[150:151], v[52:53], v[116:117], v[150:151]
	v_pk_fma_f32 v[142:143], v[50:51], v[116:117], v[142:143]
	v_pk_fma_f32 v[130:131], v[48:49], v[116:117], v[130:131]
	v_pk_fma_f32 v[128:129], v[46:47], v[116:117], v[128:129]
	v_pk_fma_f32 v[34:35], v[44:45], v[116:117], v[34:35]
	v_pk_fma_f32 v[32:33], v[42:43], v[116:117], v[32:33]
	v_lshlrev_b32_e32 v120, 16, v124
	v_and_b32_e32 v121, 0xffff0000, v124
	v_pk_fma_f32 v[152:153], v[58:59], v[118:119], v[152:153]
	v_pk_fma_f32 v[154:155], v[56:57], v[118:119], v[154:155]
	v_pk_fma_f32 v[150:151], v[54:55], v[118:119], v[150:151]
	v_pk_fma_f32 v[142:143], v[52:53], v[118:119], v[142:143]
	v_pk_fma_f32 v[130:131], v[50:51], v[118:119], v[130:131]
	v_pk_fma_f32 v[128:129], v[48:49], v[118:119], v[128:129]
	v_pk_fma_f32 v[34:35], v[46:47], v[118:119], v[34:35]
	v_pk_fma_f32 v[32:33], v[44:45], v[118:119], v[32:33]
	v_lshlrev_b32_e32 v122, 16, v125
	v_and_b32_e32 v123, 0xffff0000, v125
	v_pk_fma_f32 v[152:153], v[60:61], v[120:121], v[152:153]
	v_pk_fma_f32 v[154:155], v[58:59], v[120:121], v[154:155]
	v_pk_fma_f32 v[150:151], v[56:57], v[120:121], v[150:151]
	v_pk_fma_f32 v[142:143], v[54:55], v[120:121], v[142:143]
	v_pk_fma_f32 v[130:131], v[52:53], v[120:121], v[130:131]
	v_pk_fma_f32 v[128:129], v[50:51], v[120:121], v[128:129]
	v_pk_fma_f32 v[34:35], v[48:49], v[120:121], v[34:35]
	v_pk_fma_f32 v[32:33], v[46:47], v[120:121], v[32:33]
	v_lshlrev_b32_e32 v124, 16, v126
	v_and_b32_e32 v125, 0xffff0000, v126
	v_pk_fma_f32 v[152:153], v[62:63], v[122:123], v[152:153]
	v_pk_fma_f32 v[154:155], v[60:61], v[122:123], v[154:155]
	v_pk_fma_f32 v[150:151], v[58:59], v[122:123], v[150:151]
	v_pk_fma_f32 v[142:143], v[56:57], v[122:123], v[142:143]
	v_pk_fma_f32 v[130:131], v[54:55], v[122:123], v[130:131]
	v_pk_fma_f32 v[128:129], v[52:53], v[122:123], v[128:129]
	v_pk_fma_f32 v[34:35], v[50:51], v[122:123], v[34:35]
	v_pk_fma_f32 v[32:33], v[48:49], v[122:123], v[32:33]
	v_lshlrev_b32_e32 v126, 16, v127
	v_and_b32_e32 v127, 0xffff0000, v127
	v_pk_fma_f32 v[152:153], v[64:65], v[124:125], v[152:153]
	v_pk_fma_f32 v[154:155], v[62:63], v[124:125], v[154:155]
	v_pk_fma_f32 v[150:151], v[60:61], v[124:125], v[150:151]
	v_pk_fma_f32 v[142:143], v[58:59], v[124:125], v[142:143]
	v_pk_fma_f32 v[130:131], v[56:57], v[124:125], v[130:131]
	v_pk_fma_f32 v[128:129], v[54:55], v[124:125], v[128:129]
	v_pk_fma_f32 v[34:35], v[52:53], v[124:125], v[34:35]
	v_pk_fma_f32 v[32:33], v[50:51], v[124:125], v[32:33]
	v_lshlrev_b32_e32 v132, 16, v140
	v_and_b32_e32 v133, 0xffff0000, v140
	v_pk_fma_f32 v[152:153], v[66:67], v[126:127], v[152:153]
	v_pk_fma_f32 v[154:155], v[64:65], v[126:127], v[154:155]
	v_pk_fma_f32 v[150:151], v[62:63], v[126:127], v[150:151]
	v_pk_fma_f32 v[142:143], v[60:61], v[126:127], v[142:143]
	v_pk_fma_f32 v[130:131], v[58:59], v[126:127], v[130:131]
	v_pk_fma_f32 v[128:129], v[56:57], v[126:127], v[128:129]
	v_pk_fma_f32 v[34:35], v[54:55], v[126:127], v[34:35]
	v_pk_fma_f32 v[32:33], v[52:53], v[126:127], v[32:33]
	v_lshlrev_b32_e32 v134, 16, v141
	v_and_b32_e32 v135, 0xffff0000, v141
	v_pk_fma_f32 v[152:153], v[68:69], v[132:133], v[152:153]
	v_pk_fma_f32 v[154:155], v[66:67], v[132:133], v[154:155]
	v_pk_fma_f32 v[150:151], v[64:65], v[132:133], v[150:151]
	v_pk_fma_f32 v[142:143], v[62:63], v[132:133], v[142:143]
	v_pk_fma_f32 v[130:131], v[60:61], v[132:133], v[130:131]
	v_pk_fma_f32 v[128:129], v[58:59], v[132:133], v[128:129]
	v_pk_fma_f32 v[34:35], v[56:57], v[132:133], v[34:35]
	v_pk_fma_f32 v[32:33], v[54:55], v[132:133], v[32:33]
	v_lshlrev_b32_e32 v136, 16, v144
	v_and_b32_e32 v137, 0xffff0000, v144
	v_pk_fma_f32 v[152:153], v[70:71], v[134:135], v[152:153]
	v_pk_fma_f32 v[154:155], v[68:69], v[134:135], v[154:155]
	v_pk_fma_f32 v[150:151], v[66:67], v[134:135], v[150:151]
	v_pk_fma_f32 v[142:143], v[64:65], v[134:135], v[142:143]
	v_pk_fma_f32 v[130:131], v[62:63], v[134:135], v[130:131]
	v_pk_fma_f32 v[128:129], v[60:61], v[134:135], v[128:129]
	v_pk_fma_f32 v[34:35], v[58:59], v[134:135], v[34:35]
	v_pk_fma_f32 v[32:33], v[56:57], v[134:135], v[32:33]
	v_lshlrev_b32_e32 v138, 16, v145
	v_and_b32_e32 v139, 0xffff0000, v145
	v_pk_fma_f32 v[152:153], v[72:73], v[136:137], v[152:153]
	v_pk_fma_f32 v[154:155], v[70:71], v[136:137], v[154:155]
	v_pk_fma_f32 v[150:151], v[68:69], v[136:137], v[150:151]
	v_pk_fma_f32 v[142:143], v[66:67], v[136:137], v[142:143]
	v_pk_fma_f32 v[130:131], v[64:65], v[136:137], v[130:131]
	v_pk_fma_f32 v[128:129], v[62:63], v[136:137], v[128:129]
	v_pk_fma_f32 v[34:35], v[60:61], v[136:137], v[34:35]
	v_pk_fma_f32 v[32:33], v[58:59], v[136:137], v[32:33]
	v_lshlrev_b32_e32 v140, 16, v146
	v_and_b32_e32 v141, 0xffff0000, v146
	v_pk_fma_f32 v[152:153], v[74:75], v[138:139], v[152:153]
	v_pk_fma_f32 v[154:155], v[72:73], v[138:139], v[154:155]
	v_pk_fma_f32 v[150:151], v[70:71], v[138:139], v[150:151]
	v_pk_fma_f32 v[142:143], v[68:69], v[138:139], v[142:143]
	v_pk_fma_f32 v[130:131], v[66:67], v[138:139], v[130:131]
	v_pk_fma_f32 v[128:129], v[64:65], v[138:139], v[128:129]
	v_pk_fma_f32 v[34:35], v[62:63], v[138:139], v[34:35]
	v_pk_fma_f32 v[32:33], v[60:61], v[138:139], v[32:33]
	v_lshlrev_b32_e32 v144, 16, v147
	v_and_b32_e32 v145, 0xffff0000, v147
	v_pk_fma_f32 v[152:153], v[76:77], v[140:141], v[152:153]
	v_pk_fma_f32 v[154:155], v[74:75], v[140:141], v[154:155]
	v_pk_fma_f32 v[150:151], v[72:73], v[140:141], v[150:151]
	v_pk_fma_f32 v[142:143], v[70:71], v[140:141], v[142:143]
	v_pk_fma_f32 v[130:131], v[68:69], v[140:141], v[130:131]
	v_pk_fma_f32 v[128:129], v[66:67], v[140:141], v[128:129]
	v_pk_fma_f32 v[34:35], v[64:65], v[140:141], v[34:35]
	v_pk_fma_f32 v[32:33], v[62:63], v[140:141], v[32:33]
	v_lshlrev_b32_e32 v146, 16, v148
	v_and_b32_e32 v147, 0xffff0000, v148
	v_pk_fma_f32 v[152:153], v[78:79], v[144:145], v[152:153]
	v_pk_fma_f32 v[154:155], v[76:77], v[144:145], v[154:155]
	v_pk_fma_f32 v[150:151], v[74:75], v[144:145], v[150:151]
	v_pk_fma_f32 v[142:143], v[72:73], v[144:145], v[142:143]
	v_pk_fma_f32 v[130:131], v[70:71], v[144:145], v[130:131]
	v_pk_fma_f32 v[128:129], v[68:69], v[144:145], v[128:129]
	v_pk_fma_f32 v[34:35], v[66:67], v[144:145], v[34:35]
	v_pk_fma_f32 v[32:33], v[64:65], v[144:145], v[32:33]
	v_lshlrev_b32_e32 v148, 16, v149
	v_and_b32_e32 v149, 0xffff0000, v149
	v_pk_fma_f32 v[152:153], v[80:81], v[146:147], v[152:153]
	v_pk_fma_f32 v[154:155], v[78:79], v[146:147], v[154:155]
	v_pk_fma_f32 v[150:151], v[76:77], v[146:147], v[150:151]
	v_pk_fma_f32 v[142:143], v[74:75], v[146:147], v[142:143]
	v_pk_fma_f32 v[130:131], v[72:73], v[146:147], v[130:131]
	v_pk_fma_f32 v[128:129], v[70:71], v[146:147], v[128:129]
	v_pk_fma_f32 v[34:35], v[68:69], v[146:147], v[34:35]
	v_pk_fma_f32 v[32:33], v[66:67], v[146:147], v[32:33]
	v_lshlrev_b32_e32 v156, 16, v164
	v_and_b32_e32 v157, 0xffff0000, v164
	v_pk_fma_f32 v[152:153], v[82:83], v[148:149], v[152:153]
	v_pk_fma_f32 v[154:155], v[80:81], v[148:149], v[154:155]
	v_pk_fma_f32 v[150:151], v[78:79], v[148:149], v[150:151]
	v_pk_fma_f32 v[142:143], v[76:77], v[148:149], v[142:143]
	v_pk_fma_f32 v[130:131], v[74:75], v[148:149], v[130:131]
	v_pk_fma_f32 v[128:129], v[72:73], v[148:149], v[128:129]
	v_pk_fma_f32 v[34:35], v[70:71], v[148:149], v[34:35]
	v_pk_fma_f32 v[32:33], v[68:69], v[148:149], v[32:33]
	v_lshlrev_b32_e32 v158, 16, v165
	v_and_b32_e32 v159, 0xffff0000, v165
	v_pk_fma_f32 v[152:153], v[84:85], v[156:157], v[152:153]
	v_pk_fma_f32 v[154:155], v[82:83], v[156:157], v[154:155]
	v_pk_fma_f32 v[150:151], v[80:81], v[156:157], v[150:151]
	v_pk_fma_f32 v[142:143], v[78:79], v[156:157], v[142:143]
	v_pk_fma_f32 v[130:131], v[76:77], v[156:157], v[130:131]
	v_pk_fma_f32 v[128:129], v[74:75], v[156:157], v[128:129]
	v_pk_fma_f32 v[34:35], v[72:73], v[156:157], v[34:35]
	v_pk_fma_f32 v[32:33], v[70:71], v[156:157], v[32:33]
	v_lshlrev_b32_e32 v160, 16, v166
	v_and_b32_e32 v161, 0xffff0000, v166
	v_pk_fma_f32 v[152:153], v[86:87], v[158:159], v[152:153]
	v_pk_fma_f32 v[154:155], v[84:85], v[158:159], v[154:155]
	v_pk_fma_f32 v[150:151], v[82:83], v[158:159], v[150:151]
	v_pk_fma_f32 v[142:143], v[80:81], v[158:159], v[142:143]
	v_pk_fma_f32 v[130:131], v[78:79], v[158:159], v[130:131]
	v_pk_fma_f32 v[128:129], v[76:77], v[158:159], v[128:129]
	v_pk_fma_f32 v[34:35], v[74:75], v[158:159], v[34:35]
	v_pk_fma_f32 v[32:33], v[72:73], v[158:159], v[32:33]
	v_lshlrev_b32_e32 v162, 16, v167
	v_and_b32_e32 v163, 0xffff0000, v167
	v_pk_fma_f32 v[152:153], v[88:89], v[160:161], v[152:153]
	v_pk_fma_f32 v[154:155], v[86:87], v[160:161], v[154:155]
	v_pk_fma_f32 v[150:151], v[84:85], v[160:161], v[150:151]
	v_pk_fma_f32 v[142:143], v[82:83], v[160:161], v[142:143]
	v_pk_fma_f32 v[130:131], v[80:81], v[160:161], v[130:131]
	v_pk_fma_f32 v[128:129], v[78:79], v[160:161], v[128:129]
	v_pk_fma_f32 v[34:35], v[76:77], v[160:161], v[34:35]
	v_pk_fma_f32 v[32:33], v[74:75], v[160:161], v[32:33]
	v_lshlrev_b32_e32 v164, 16, v168
	v_and_b32_e32 v165, 0xffff0000, v168
	v_pk_fma_f32 v[152:153], v[90:91], v[162:163], v[152:153]
	v_pk_fma_f32 v[154:155], v[88:89], v[162:163], v[154:155]
	v_pk_fma_f32 v[150:151], v[86:87], v[162:163], v[150:151]
	v_pk_fma_f32 v[142:143], v[84:85], v[162:163], v[142:143]
	v_pk_fma_f32 v[130:131], v[82:83], v[162:163], v[130:131]
	v_pk_fma_f32 v[128:129], v[80:81], v[162:163], v[128:129]
	v_pk_fma_f32 v[34:35], v[78:79], v[162:163], v[34:35]
	v_pk_fma_f32 v[32:33], v[76:77], v[162:163], v[32:33]
	v_lshlrev_b32_e32 v166, 16, v169
	v_and_b32_e32 v167, 0xffff0000, v169
	v_pk_fma_f32 v[152:153], v[92:93], v[164:165], v[152:153]
	v_pk_fma_f32 v[154:155], v[90:91], v[164:165], v[154:155]
	v_pk_fma_f32 v[150:151], v[88:89], v[164:165], v[150:151]
	v_pk_fma_f32 v[142:143], v[86:87], v[164:165], v[142:143]
	v_pk_fma_f32 v[130:131], v[84:85], v[164:165], v[130:131]
	v_pk_fma_f32 v[128:129], v[82:83], v[164:165], v[128:129]
	v_pk_fma_f32 v[34:35], v[80:81], v[164:165], v[34:35]
	v_pk_fma_f32 v[32:33], v[78:79], v[164:165], v[32:33]
	v_lshlrev_b32_e32 v168, 16, v170
	v_and_b32_e32 v169, 0xffff0000, v170
	v_pk_fma_f32 v[152:153], v[94:95], v[166:167], v[152:153]
	v_pk_fma_f32 v[154:155], v[92:93], v[166:167], v[154:155]
	v_pk_fma_f32 v[150:151], v[90:91], v[166:167], v[150:151]
	v_pk_fma_f32 v[142:143], v[88:89], v[166:167], v[142:143]
	v_pk_fma_f32 v[130:131], v[86:87], v[166:167], v[130:131]
	v_pk_fma_f32 v[128:129], v[84:85], v[166:167], v[128:129]
	v_pk_fma_f32 v[34:35], v[82:83], v[166:167], v[34:35]
	v_pk_fma_f32 v[32:33], v[80:81], v[166:167], v[32:33]
	v_lshlrev_b32_e32 v170, 16, v171
	v_and_b32_e32 v171, 0xffff0000, v171
	v_pk_fma_f32 v[152:153], v[96:97], v[168:169], v[152:153]
	v_pk_fma_f32 v[154:155], v[94:95], v[168:169], v[154:155]
	v_pk_fma_f32 v[150:151], v[92:93], v[168:169], v[150:151]
	v_pk_fma_f32 v[142:143], v[90:91], v[168:169], v[142:143]
	v_pk_fma_f32 v[130:131], v[88:89], v[168:169], v[130:131]
	v_pk_fma_f32 v[128:129], v[86:87], v[168:169], v[128:129]
	v_pk_fma_f32 v[34:35], v[84:85], v[168:169], v[34:35]
	v_pk_fma_f32 v[32:33], v[82:83], v[168:169], v[32:33]
	v_lshlrev_b32_e32 v172, 16, v173
	v_and_b32_e32 v173, 0xffff0000, v173
	v_pk_fma_f32 v[154:155], v[96:97], v[170:171], v[154:155]
	v_pk_fma_f32 v[150:151], v[94:95], v[170:171], v[150:151]
	v_pk_fma_f32 v[142:143], v[92:93], v[170:171], v[142:143]
	v_pk_fma_f32 v[130:131], v[90:91], v[170:171], v[130:131]
	v_pk_fma_f32 v[128:129], v[88:89], v[170:171], v[128:129]
	v_pk_fma_f32 v[34:35], v[86:87], v[170:171], v[34:35]
	v_pk_fma_f32 v[32:33], v[84:85], v[170:171], v[32:33]
	v_pk_mul_f32 v[112:113], v[152:153], v[152:153]
	v_pk_fma_f32 v[150:151], v[96:97], v[172:173], v[150:151]
	v_pk_fma_f32 v[142:143], v[94:95], v[172:173], v[142:143]
	v_pk_fma_f32 v[130:131], v[92:93], v[172:173], v[130:131]
	v_pk_fma_f32 v[128:129], v[90:91], v[172:173], v[128:129]
	v_pk_fma_f32 v[34:35], v[88:89], v[172:173], v[34:35]
	v_pk_fma_f32 v[32:33], v[86:87], v[172:173], v[32:33]
	v_add_f32_e32 v115, v112, v113
	v_pk_mul_f32 v[112:113], v[154:155], v[154:155]
	v_lshlrev_b32_e32 v176, 16, v177
	v_and_b32_e32 v177, 0xffff0000, v177
	v_pk_fma_f32 v[142:143], v[96:97], v[174:175], v[142:143]
	v_pk_fma_f32 v[130:131], v[94:95], v[174:175], v[130:131]
	v_pk_fma_f32 v[128:129], v[92:93], v[174:175], v[128:129]
	v_pk_fma_f32 v[34:35], v[90:91], v[174:175], v[34:35]
	v_pk_fma_f32 v[32:33], v[88:89], v[174:175], v[32:33]
	v_add_f32_e32 v117, v112, v113
	v_pk_mul_f32 v[112:113], v[150:151], v[150:151]
	v_pk_fma_f32 v[130:131], v[96:97], v[176:177], v[130:131]
	v_pk_fma_f32 v[128:129], v[94:95], v[176:177], v[128:129]
	v_pk_fma_f32 v[34:35], v[92:93], v[176:177], v[34:35]
	v_pk_fma_f32 v[32:33], v[90:91], v[176:177], v[32:33]
	v_add_f32_e32 v119, v112, v113
	v_pk_mul_f32 v[112:113], v[142:143], v[142:143]
	v_lshlrev_b32_e32 v182, 16, v183
	v_and_b32_e32 v183, 0xffff0000, v183
	v_pk_fma_f32 v[128:129], v[96:97], v[180:181], v[128:129]
	v_pk_fma_f32 v[34:35], v[94:95], v[180:181], v[34:35]
	v_pk_fma_f32 v[32:33], v[92:93], v[180:181], v[32:33]
	v_add_f32_e32 v121, v112, v113
	v_pk_mul_f32 v[112:113], v[130:131], v[130:131]
	v_pk_fma_f32 v[34:35], v[96:97], v[182:183], v[34:35]
	v_pk_fma_f32 v[32:33], v[94:95], v[182:183], v[32:33]
	v_add_f32_e32 v123, v112, v113
	v_pk_mul_f32 v[112:113], v[128:129], v[128:129]
	v_pk_fma_f32 v[32:33], v[96:97], v[178:179], v[32:33]
	v_add_f32_e32 v125, v112, v113
	v_pk_mul_f32 v[112:113], v[34:35], v[34:35]
	v_add_f32_e32 v114, v152, v153
	v_add_f32_e32 v122, v130, v131
	v_add_f32_e32 v127, v112, v113
	v_pk_mul_f32 v[112:113], v[32:33], v[32:33]
	v_add_f32_e32 v116, v154, v155
	v_add_f32_e32 v112, v112, v113
	v_add_f32_e32 v124, v128, v129
	v_add_f32_e32 v118, v150, v151
	v_add_f32_e32 v126, v34, v35
	v_add_f32_e32 v120, v142, v143
	v_add_f32_e32 v132, v32, v33
	s_nop 1
	v_permlane32_swap_b32_e32 v114, v122
	v_permlane32_swap_b32_e32 v115, v123
	v_permlane32_swap_b32_e32 v116, v124
	v_permlane32_swap_b32_e32 v117, v125
	v_permlane32_swap_b32_e32 v118, v126
	v_permlane32_swap_b32_e32 v119, v127
	v_permlane32_swap_b32_e32 v120, v132
	v_permlane32_swap_b32_e32 v121, v112
	v_add_f32_e32 v114, v114, v122
	v_add_f32_e32 v115, v115, v123
	v_add_f32_e32 v116, v116, v124
	v_add_f32_e32 v117, v117, v125
	v_add_f32_e32 v118, v118, v126
	v_add_f32_e32 v119, v119, v127
	v_add_f32_e32 v120, v120, v132
	v_add_f32_e32 v121, v121, v112
	s_nop 1
	v_permlane16_swap_b32_e32 v114, v118
	v_permlane16_swap_b32_e32 v115, v119
	v_permlane16_swap_b32_e32 v116, v120
	v_permlane16_swap_b32_e32 v117, v121
	v_add_f32_e32 v114, v114, v118
	v_add_f32_e32 v115, v115, v119
	v_add_f32_e32 v116, v116, v120
	v_add_f32_e32 v117, v117, v121
	s_nop 1
	v_add_f32_dpp v122, v114, v114 row_ror:8 row_mask:0xf bank_mask:0xf
	v_add_f32_dpp v123, v116, v116 row_ror:8 row_mask:0xf bank_mask:0xf
	v_add_f32_dpp v124, v115, v115 row_ror:8 row_mask:0xf bank_mask:0xf
	v_add_f32_dpp v125, v117, v117 row_ror:8 row_mask:0xf bank_mask:0xf
	v_cndmask_b32_e64 v114, v123, v122, s[6:7]
	v_cndmask_b32_e64 v115, v125, v124, s[6:7]
	s_nop 1
	v_add_f32_dpp v122, v114, v114 row_shl:4 row_mask:0xf bank_mask:0xf
	v_add_f32_dpp v123, v115, v115 row_shr:4 row_mask:0xf bank_mask:0xf
	v_cndmask_b32_e64 v112, v123, v122, s[8:9]
	s_nop 1
	v_add_f32_dpp v112, v112, v112 quad_perm:[2,3,0,1] row_mask:0xf bank_mask:0xf
	s_nop 1
	v_add_f32_dpp v112, v112, v112 quad_perm:[1,0,3,2] row_mask:0xf bank_mask:0xf
	s_and_saveexec_b64 s[48:49], s[10:11]
	s_cbranch_execz .LBB0_464
	ds_write_b32 v185, v112
